# q4c + non-temporal stores for the residual-stream epilogue (w_out, w2 latent units)
# baseline (speedup 1.0000x reference)
;     __device__ __forceinline__ void operator()(const f32x4 (&acc)[2][2][4][2], const Unit& u, int wr, int wc, int fr, int fq) const {
;         const bool lat = u.pm < 64; const int r = lat ? (u.pm >> 3) : 8;
;         const float* s = lat ? src_lat : src_ctx; float* d = lat ? dst_lat : dst_ctx;
;         const int row0 = (lat ? u.pm : u.pm - 64) * BM + wr * 64 + fr, col0 = u.pn * BM + wc * 32 + 4 * fq;
;         const float* g = gate + (size_t)r * 12288 + col0;
;         f32x4 gv[2][2];
; #pragma unroll
;         for (int bj = 0; bj < 2; ++bj)
; #pragma unroll
;             for (int n = 0; n < 2; ++n) gv[bj][n] = *(const f32x4*)(g + bj * HALF + n * 16);
;         f32x4 xc[2][2], xn[2][2];
; #pragma unroll
;         for (int bj = 0; bj < 2; ++bj)
; #pragma unroll
;             for (int n = 0; n < 2; ++n) xc[bj][n] = *(const f32x4*)(s + (size_t)row0 * DM + col0 + bj * HALF + n * 16);
; #pragma unroll
;         for (int gi = 0; gi < 8; ++gi) { const int ai = gi >> 2, m = gi & 3; const size_t off = (size_t)(row0 + ai * HALF + m * 16) * DM + col0;
;             if (gi + 1 < 8) { const int ai2 = (gi + 1) >> 2, m2 = (gi + 1) & 3; const size_t off2 = (size_t)(row0 + ai2 * HALF + m2 * 16) * DM + col0;
; #pragma unroll
;                 for (int bj = 0; bj < 2; ++bj)
; #pragma unroll
;                     for (int n = 0; n < 2; ++n) xn[bj][n] = *(const f32x4*)(s + off2 + bj * HALF + n * 16); }
; #pragma unroll
;             for (int bj = 0; bj < 2; ++bj)
; #pragma unroll
;                 for (int n = 0; n < 2; ++n) *(f32x4*)(d + off + bj * HALF + n * 16) = xc[bj][n] + gv[bj][n] * acc[ai][bj][m][n];
; #pragma unroll
;             for (int bj = 0; bj < 2; ++bj)
; #pragma unroll
;                 for (int n = 0; n < 2; ++n) xc[bj][n] = xn[bj][n]; }
;     }
.LBB0_36:
	s_lshl_b32 s8, s8, 8
	s_add_i32 s25, s8, 0xffffc000
	s_and_b64 s[38:39], s[50:51], exec
	s_cselect_b32 s8, s8, s25
	v_add_u32_e32 v152, s8, v162
	v_lshl_or_b32 v66, s70, 8, v164
	s_lshl_b64 s[38:39], s[52:53], 2
	v_ashrrev_i32_e32 v153, 31, v152
	s_add_u32 s38, s64, s38
	v_ashrrev_i32_e32 v67, 31, v66
	v_lshlrev_b64 v[194:195], 13, v[152:153]
	s_addc_u32 s39, s65, s39
	v_lshlrev_b64 v[160:161], 2, v[66:67]
	v_lshl_add_u64 v[154:155], s[28:29], 0, v[194:195]
	v_lshl_add_u64 v[66:67], s[38:39], 0, v[160:161]
	v_lshl_add_u64 v[174:175], v[154:155], 0, v[160:161]
	global_load_dwordx4 v[78:81], v[66:67], off
	global_load_dwordx4 v[74:77], v[66:67], off offset:64
	global_load_dwordx4 v[70:73], v[66:67], off offset:512
	s_nop 0
	global_load_dwordx4 v[66:69], v[66:67], off offset:576
	s_nop 0
	global_load_dwordx4 v[154:157], v[174:175], off
	global_load_dwordx4 v[166:169], v[174:175], off offset:64
	global_load_dwordx4 v[170:173], v[174:175], off offset:512
	s_nop 0
	global_load_dwordx4 v[174:177], v[174:175], off offset:576
	v_or_b32_e32 v178, 16, v152
	v_ashrrev_i32_e32 v179, 31, v178
	v_lshl_add_u64 v[160:161], s[28:29], 0, v[160:161]
	v_lshlrev_b64 v[178:179], 13, v[178:179]
	v_lshl_add_u64 v[196:197], v[160:161], 0, v[178:179]
	global_load_dwordx4 v[178:181], v[196:197], off
	global_load_dwordx4 v[182:185], v[196:197], off offset:64
	global_load_dwordx4 v[186:189], v[196:197], off offset:512
	global_load_dwordx4 v[190:193], v[196:197], off offset:576
	v_lshl_add_u64 v[194:195], v[160:161], 0, v[194:195]
	s_mov_b64 s[28:29], 0x100000
	s_mov_b32 s70, s24
	s_mov_b32 s8, s26
	s_mov_b64 s[50:51], s[48:49]
	s_waitcnt vmcnt(0)
	v_pk_fma_f32 v[144:145], v[144:145], v[80:81], v[156:157]
	v_pk_fma_f32 v[142:143], v[142:143], v[78:79], v[154:155]
	v_pk_fma_f32 v[140:141], v[140:141], v[76:77], v[168:169]
	v_pk_fma_f32 v[132:133], v[132:133], v[68:69], v[176:177]
	v_pk_fma_f32 v[130:131], v[130:131], v[66:67], v[174:175]
	global_store_dwordx4 v[194:195], v[130:133], off offset:576 nt
	v_pk_fma_f32 v[138:139], v[138:139], v[74:75], v[166:167]
	v_pk_fma_f32 v[136:137], v[136:137], v[72:73], v[172:173]
	v_or_b32_e32 v130, 32, v152
	v_ashrrev_i32_e32 v131, 31, v130
	v_pk_fma_f32 v[134:135], v[134:135], v[70:71], v[170:171]
	v_lshlrev_b64 v[130:131], 13, v[130:131]
	global_store_dwordx4 v[194:195], v[142:145], off nt
	global_store_dwordx4 v[194:195], v[138:141], off offset:64 nt
	global_store_dwordx4 v[194:195], v[134:137], off offset:512 nt
	v_lshl_add_u64 v[154:155], v[160:161], 0, v[130:131]
	v_pk_fma_f32 v[116:117], v[116:117], v[68:69], v[192:193]
	v_pk_fma_f32 v[114:115], v[114:115], v[66:67], v[190:191]
	global_load_dwordx4 v[130:133], v[154:155], off
	global_load_dwordx4 v[134:137], v[154:155], off offset:64
	global_load_dwordx4 v[138:141], v[154:155], off offset:512
	global_load_dwordx4 v[142:145], v[154:155], off offset:576
	v_pk_fma_f32 v[128:129], v[128:129], v[80:81], v[180:181]
	global_store_dwordx4 v[196:197], v[114:117], off offset:576 nt
	v_pk_fma_f32 v[126:127], v[126:127], v[78:79], v[178:179]
	v_pk_fma_f32 v[124:125], v[124:125], v[76:77], v[184:185]
	v_or_b32_e32 v114, 48, v152
	v_ashrrev_i32_e32 v115, 31, v114
	v_pk_fma_f32 v[122:123], v[122:123], v[74:75], v[182:183]
	v_pk_fma_f32 v[120:121], v[120:121], v[72:73], v[188:189]
	v_pk_fma_f32 v[118:119], v[118:119], v[70:71], v[186:187]
	v_lshlrev_b64 v[114:115], 13, v[114:115]
	global_store_dwordx4 v[196:197], v[126:129], off nt
	global_store_dwordx4 v[196:197], v[122:125], off offset:64 nt
	global_store_dwordx4 v[196:197], v[118:121], off offset:512 nt
	v_lshl_add_u64 v[156:157], v[160:161], 0, v[114:115]
	global_load_dwordx4 v[114:117], v[156:157], off
	global_load_dwordx4 v[118:121], v[156:157], off offset:64
	global_load_dwordx4 v[122:125], v[156:157], off offset:512
	global_load_dwordx4 v[126:129], v[156:157], off offset:576
	s_waitcnt vmcnt(0)
;     __device__ __forceinline__ void operator()(const f32x4 (&acc)[2][2][4][2], const Unit& u, int wr, int wc, int fr, int fq) const {
;     ...
;         for (int gi = 0; gi < 8; ++gi) { const int ai = gi >> 2, m = gi & 3; const size_t off = (size_t)(row0 + ai * HALF + m * 16) * DM + col0;
;             if (gi + 1 < 8) { const int ai2 = (gi + 1) >> 2, m2 = (gi + 1) & 3; const size_t off2 = (size_t)(row0 + ai2 * HALF + m2 * 16) * DM + col0;
; #pragma unroll
;                 for (int bj = 0; bj < 2; ++bj)
; #pragma unroll
;                     for (int n = 0; n < 2; ++n) xn[bj][n] = *(const f32x4*)(s + off2 + bj * HALF + n * 16); }
; #pragma unroll
;             for (int bj = 0; bj < 2; ++bj)
; #pragma unroll
;                 for (int n = 0; n < 2; ++n) *(f32x4*)(d + off + bj * HALF + n * 16) = xc[bj][n] + gv[bj][n] * acc[ai][bj][m][n];
; #pragma unroll
;             for (int bj = 0; bj < 2; ++bj)
; #pragma unroll
;                 for (int n = 0; n < 2; ++n) xc[bj][n] = xn[bj][n]; }
;     }
	v_pk_fma_f32 v[112:113], v[112:113], v[80:81], v[132:133]
	v_pk_fma_f32 v[110:111], v[110:111], v[78:79], v[130:131]
	v_pk_fma_f32 v[108:109], v[108:109], v[76:77], v[136:137]
	v_pk_fma_f32 v[106:107], v[106:107], v[74:75], v[134:135]
	v_pk_fma_f32 v[96:97], v[96:97], v[72:73], v[140:141]
	v_pk_fma_f32 v[94:95], v[94:95], v[70:71], v[138:139]
	v_pk_fma_f32 v[92:93], v[92:93], v[68:69], v[144:145]
	v_pk_fma_f32 v[90:91], v[90:91], v[66:67], v[142:143]
	v_add_co_u32_e32 v140, vcc, s93, v194
	global_store_dwordx4 v[154:155], v[110:113], off nt
	global_store_dwordx4 v[154:155], v[106:109], off offset:64 nt
	global_store_dwordx4 v[154:155], v[94:97], off offset:512 nt
	global_store_dwordx4 v[154:155], v[90:93], off offset:576 nt
	v_addc_co_u32_e32 v141, vcc, 0, v195, vcc
	v_lshl_add_u64 v[138:139], v[194:195], 0, s[28:29]
	global_load_dwordx4 v[106:109], v[140:141], off
	global_load_dwordx4 v[110:113], v[138:139], off offset:64
	global_load_dwordx4 v[130:133], v[138:139], off offset:512
	global_load_dwordx4 v[134:137], v[138:139], off offset:576
	v_pk_fma_f32 v[84:85], v[84:85], v[68:69], v[128:129]
	v_pk_fma_f32 v[82:83], v[82:83], v[66:67], v[126:127]
	global_store_dwordx4 v[156:157], v[82:85], off offset:576 nt
	v_pk_fma_f32 v[92:93], v[104:105], v[80:81], v[116:117]
	v_pk_fma_f32 v[90:91], v[102:103], v[78:79], v[114:115]
	v_add_u32_e32 v82, 0x90, v152
	v_ashrrev_i32_e32 v83, 31, v82
	global_store_dwordx4 v[156:157], v[90:93], off nt
	v_pk_fma_f32 v[88:89], v[88:89], v[72:73], v[124:125]
	v_pk_fma_f32 v[86:87], v[86:87], v[70:71], v[122:123]
	v_pk_fma_f32 v[92:93], v[100:101], v[76:77], v[120:121]
	v_pk_fma_f32 v[90:91], v[98:99], v[74:75], v[118:119]
	v_lshlrev_b64 v[82:83], 13, v[82:83]
	global_store_dwordx4 v[156:157], v[90:93], off offset:64 nt
	global_store_dwordx4 v[156:157], v[86:89], off offset:512 nt
	v_lshl_add_u64 v[100:101], v[160:161], 0, v[82:83]
	global_load_dwordx4 v[94:97], v[100:101], off
	global_load_dwordx4 v[90:93], v[100:101], off offset:64
	global_load_dwordx4 v[86:89], v[100:101], off offset:512
	global_load_dwordx4 v[82:85], v[100:101], off offset:576
	s_and_b64 vcc, exec, s[40:41]
	s_mov_b64 s[28:29], s[42:43]
	s_waitcnt vmcnt(0)
	v_pk_fma_f32 v[64:65], v[64:65], v[80:81], v[108:109]
	v_pk_fma_f32 v[62:63], v[62:63], v[78:79], v[106:107]
	v_pk_fma_f32 v[60:61], v[60:61], v[76:77], v[112:113]
	v_pk_fma_f32 v[52:53], v[52:53], v[68:69], v[136:137]
	v_pk_fma_f32 v[50:51], v[50:51], v[66:67], v[134:135]
	global_store_dwordx4 v[138:139], v[50:53], off offset:576 nt
	v_pk_fma_f32 v[58:59], v[58:59], v[74:75], v[110:111]
	v_pk_fma_f32 v[56:57], v[56:57], v[72:73], v[132:133]
	v_add_u32_e32 v50, 0xa0, v152
	v_ashrrev_i32_e32 v51, 31, v50
	v_pk_fma_f32 v[54:55], v[54:55], v[70:71], v[130:131]
	v_lshlrev_b64 v[50:51], 13, v[50:51]
	global_store_dwordx4 v[140:141], v[62:65], off nt
	global_store_dwordx4 v[138:139], v[58:61], off offset:64 nt
	global_store_dwordx4 v[138:139], v[54:57], off offset:512 nt
	v_lshl_add_u64 v[98:99], v[160:161], 0, v[50:51]
	global_load_dwordx4 v[62:65], v[98:99], off
	global_load_dwordx4 v[58:61], v[98:99], off offset:64
	global_load_dwordx4 v[54:57], v[98:99], off offset:512
	global_load_dwordx4 v[50:53], v[98:99], off offset:576
	v_pk_fma_f32 v[48:49], v[48:49], v[80:81], v[96:97]
	v_pk_fma_f32 v[46:47], v[46:47], v[78:79], v[94:95]
	v_pk_fma_f32 v[44:45], v[44:45], v[76:77], v[92:93]
	v_pk_fma_f32 v[36:37], v[36:37], v[68:69], v[84:85]
	v_pk_fma_f32 v[34:35], v[34:35], v[66:67], v[82:83]
	global_store_dwordx4 v[100:101], v[34:37], off offset:576 nt
	v_pk_fma_f32 v[42:43], v[42:43], v[74:75], v[90:91]
	v_pk_fma_f32 v[40:41], v[40:41], v[72:73], v[88:89]
	v_add_u32_e32 v34, 0xb0, v152
	v_ashrrev_i32_e32 v35, 31, v34
	v_pk_fma_f32 v[38:39], v[38:39], v[70:71], v[86:87]
	v_lshlrev_b64 v[34:35], 13, v[34:35]
	global_store_dwordx4 v[100:101], v[46:49], off nt
	global_store_dwordx4 v[100:101], v[42:45], off offset:64 nt
	global_store_dwordx4 v[100:101], v[38:41], off offset:512 nt
	v_lshl_add_u64 v[82:83], v[160:161], 0, v[34:35]
	global_load_dwordx4 v[46:49], v[82:83], off
	global_load_dwordx4 v[42:45], v[82:83], off offset:64
	global_load_dwordx4 v[38:41], v[82:83], off offset:512
	global_load_dwordx4 v[34:37], v[82:83], off offset:576
	s_waitcnt vmcnt(0)
	v_pk_fma_f32 v[32:33], v[32:33], v[80:81], v[64:65]
	v_pk_fma_f32 v[30:31], v[30:31], v[78:79], v[62:63]
	v_pk_fma_f32 v[28:29], v[28:29], v[76:77], v[60:61]
	v_pk_fma_f32 v[12:13], v[12:13], v[68:69], v[52:53]
	v_pk_fma_f32 v[10:11], v[10:11], v[66:67], v[50:51]
	global_store_dwordx4 v[98:99], v[10:13], off offset:576 nt
	v_pk_fma_f32 v[26:27], v[26:27], v[74:75], v[58:59]
	v_pk_fma_f32 v[20:21], v[20:21], v[72:73], v[56:57]
	v_pk_fma_f32 v[18:19], v[18:19], v[70:71], v[54:55]
	global_store_dwordx4 v[98:99], v[30:33], off nt
	global_store_dwordx4 v[98:99], v[26:29], off offset:64 nt
	global_store_dwordx4 v[98:99], v[18:21], off offset:512 nt
	v_pk_fma_f32 v[12:13], v[24:25], v[80:81], v[48:49]
	v_pk_fma_f32 v[10:11], v[22:23], v[78:79], v[46:47]
	global_store_dwordx4 v[82:83], v[10:13], off nt
	v_pk_fma_f32 v[8:9], v[8:9], v[72:73], v[40:41]
	v_pk_fma_f32 v[6:7], v[6:7], v[70:71], v[38:39]
	v_pk_fma_f32 v[12:13], v[16:17], v[76:77], v[44:45]
	v_pk_fma_f32 v[10:11], v[14:15], v[74:75], v[42:43]
	v_pk_fma_f32 v[4:5], v[4:5], v[68:69], v[36:37]
	v_pk_fma_f32 v[2:3], v[2:3], v[66:67], v[34:35]
	global_store_dwordx4 v[82:83], v[10:13], off offset:64 nt
	global_store_dwordx4 v[82:83], v[6:9], off offset:512 nt
	global_store_dwordx4 v[82:83], v[2:5], off offset:576 nt
	s_cbranch_vccnz .LBB0_47

;     __device__ __forceinline__ void operator()(const f32x4 (&acc)[2][2][4][2], const Unit& u, int wr, int wc, int fr, int fq) const {
;         const bool lat = u.pm < 64; const int r = lat ? (u.pm >> 3) : 8;
;         const float* s = lat ? src_lat : src_ctx; float* d = lat ? dst_lat : dst_ctx;
;         const int row0 = (lat ? u.pm : u.pm - 64) * BM + wr * 64 + fr, col0 = u.pn * BM + wc * 32 + 4 * fq;
;         const float* g = gate + (size_t)r * 12288 + col0;
;         f32x4 gv[2][2];
; #pragma unroll
;         for (int bj = 0; bj < 2; ++bj)
; #pragma unroll
;             for (int n = 0; n < 2; ++n) gv[bj][n] = *(const f32x4*)(g + bj * HALF + n * 16);
;         f32x4 xc[2][2], xn[2][2];
; #pragma unroll
;         for (int bj = 0; bj < 2; ++bj)
; #pragma unroll
;             for (int n = 0; n < 2; ++n) xc[bj][n] = *(const f32x4*)(s + (size_t)row0 * DM + col0 + bj * HALF + n * 16);
; #pragma unroll
;         for (int gi = 0; gi < 8; ++gi) { const int ai = gi >> 2, m = gi & 3; const size_t off = (size_t)(row0 + ai * HALF + m * 16) * DM + col0;
;             if (gi + 1 < 8) { const int ai2 = (gi + 1) >> 2, m2 = (gi + 1) & 3; const size_t off2 = (size_t)(row0 + ai2 * HALF + m2 * 16) * DM + col0;
; #pragma unroll
;                 for (int bj = 0; bj < 2; ++bj)
; #pragma unroll
;                     for (int n = 0; n < 2; ++n) xn[bj][n] = *(const f32x4*)(s + off2 + bj * HALF + n * 16); }
; #pragma unroll
;             for (int bj = 0; bj < 2; ++bj)
; #pragma unroll
;                 for (int n = 0; n < 2; ++n) *(f32x4*)(d + off + bj * HALF + n * 16) = xc[bj][n] + gv[bj][n] * acc[ai][bj][m][n];
; #pragma unroll
;             for (int bj = 0; bj < 2; ++bj)
; #pragma unroll
;                 for (int n = 0; n < 2; ++n) xc[bj][n] = xn[bj][n]; }
;     }
.LBB0_91:
	s_lshl_b32 s8, s8, 8
	s_add_i32 s49, s8, 0xffffc000
	s_and_b64 s[38:39], s[58:59], exec
	s_cselect_b32 s8, s8, s49
	v_add_u32_e32 v162, s8, v168
	v_lshl_or_b32 v98, s76, 8, v170
	s_lshl_b64 s[38:39], s[60:61], 2
	v_ashrrev_i32_e32 v163, 31, v162
	s_add_u32 s38, s30, s38
	v_ashrrev_i32_e32 v99, 31, v98
	v_lshlrev_b64 v[164:165], 13, v[162:163]
	s_addc_u32 s39, s71, s39
	v_lshlrev_b64 v[152:153], 2, v[98:99]
	v_lshl_add_u64 v[154:155], s[56:57], 0, v[164:165]
	v_lshl_add_u64 v[98:99], s[38:39], 0, v[152:153]
	v_lshl_add_u64 v[160:161], v[154:155], 0, v[152:153]
	global_load_dwordx4 v[110:113], v[98:99], off
	global_load_dwordx4 v[106:109], v[98:99], off offset:64
	global_load_dwordx4 v[102:105], v[98:99], off offset:512
	s_nop 0
	global_load_dwordx4 v[98:101], v[98:99], off offset:576
	s_nop 0
	global_load_dwordx4 v[154:157], v[160:161], off
	global_load_dwordx4 v[172:175], v[160:161], off offset:64
	global_load_dwordx4 v[176:179], v[160:161], off offset:512
	global_load_dwordx4 v[180:183], v[160:161], off offset:576
	v_or_b32_e32 v166, 16, v162
	v_ashrrev_i32_e32 v167, 31, v166
	v_lshl_add_u64 v[160:161], s[56:57], 0, v[152:153]
	v_lshlrev_b64 v[200:201], 13, v[166:167]
	v_lshl_add_u64 v[166:167], v[160:161], 0, v[200:201]
	global_load_dwordx4 v[184:187], v[166:167], off
	global_load_dwordx4 v[188:191], v[166:167], off offset:64
	global_load_dwordx4 v[192:195], v[166:167], off offset:512
	global_load_dwordx4 v[196:199], v[166:167], off offset:576
	v_lshl_add_u64 v[152:153], s[28:29], 0, v[152:153]
	v_lshl_add_u64 v[166:167], v[152:153], 0, v[164:165]
	s_mov_b64 s[28:29], 0x100000
	s_and_b64 vcc, exec, s[40:41]
	s_mov_b32 s76, s48
	s_mov_b32 s8, s50
	s_mov_b64 s[56:57], s[54:55]
	s_waitcnt vmcnt(0)
	v_pk_fma_f32 v[144:145], v[144:145], v[112:113], v[156:157]
	v_pk_fma_f32 v[142:143], v[142:143], v[110:111], v[154:155]
	v_pk_fma_f32 v[140:141], v[140:141], v[108:109], v[174:175]
	v_pk_fma_f32 v[132:133], v[132:133], v[100:101], v[182:183]
	v_pk_fma_f32 v[130:131], v[130:131], v[98:99], v[180:181]
	global_store_dwordx4 v[166:167], v[130:133], off offset:576 nt
	v_pk_fma_f32 v[138:139], v[138:139], v[106:107], v[172:173]
	v_pk_fma_f32 v[136:137], v[136:137], v[104:105], v[178:179]
	v_or_b32_e32 v130, 32, v162
	v_pk_fma_f32 v[134:135], v[134:135], v[102:103], v[176:177]
	v_ashrrev_i32_e32 v131, 31, v130
	global_store_dwordx4 v[166:167], v[142:145], off nt
	global_store_dwordx4 v[166:167], v[138:141], off offset:64 nt
	global_store_dwordx4 v[166:167], v[134:137], off offset:512 nt
	v_lshlrev_b64 v[166:167], 13, v[130:131]
	v_lshl_add_u64 v[130:131], v[160:161], 0, v[166:167]
	v_lshl_add_u64 v[154:155], v[152:153], 0, v[200:201]
	v_pk_fma_f32 v[116:117], v[116:117], v[100:101], v[198:199]
	v_pk_fma_f32 v[114:115], v[114:115], v[98:99], v[196:197]
	global_load_dwordx4 v[142:145], v[130:131], off
	global_load_dwordx4 v[138:141], v[130:131], off offset:64
	global_load_dwordx4 v[134:137], v[130:131], off offset:512
	s_nop 0
	global_load_dwordx4 v[130:133], v[130:131], off offset:576
	v_pk_fma_f32 v[128:129], v[128:129], v[112:113], v[186:187]
	global_store_dwordx4 v[154:155], v[114:117], off offset:576 nt
	v_pk_fma_f32 v[126:127], v[126:127], v[110:111], v[184:185]
	global_store_dwordx4 v[154:155], v[126:129], off nt
	v_or_b32_e32 v114, 48, v162
	v_ashrrev_i32_e32 v115, 31, v114
	v_pk_fma_f32 v[124:125], v[124:125], v[108:109], v[190:191]
	v_pk_fma_f32 v[122:123], v[122:123], v[106:107], v[188:189]
	v_pk_fma_f32 v[120:121], v[120:121], v[104:105], v[194:195]
	v_pk_fma_f32 v[118:119], v[118:119], v[102:103], v[192:193]
	v_lshlrev_b64 v[128:129], 13, v[114:115]
	global_store_dwordx4 v[154:155], v[122:125], off offset:64 nt
	global_store_dwordx4 v[154:155], v[118:121], off offset:512 nt
	v_lshl_add_u64 v[114:115], v[160:161], 0, v[128:129]
	global_load_dwordx4 v[116:119], v[114:115], off
	global_load_dwordx4 v[120:123], v[114:115], off offset:64
	global_load_dwordx4 v[124:127], v[114:115], off offset:512
	global_load_dwordx4 v[154:157], v[114:115], off offset:576
	v_lshl_add_u64 v[114:115], v[152:153], 0, v[166:167]
	v_lshl_add_u64 v[128:129], v[152:153], 0, v[128:129]
	s_waitcnt vmcnt(0)
;     __device__ __forceinline__ void operator()(const f32x4 (&acc)[2][2][4][2], const Unit& u, int wr, int wc, int fr, int fq) const {
;     ...
;         for (int gi = 0; gi < 8; ++gi) { const int ai = gi >> 2, m = gi & 3; const size_t off = (size_t)(row0 + ai * HALF + m * 16) * DM + col0;
;             if (gi + 1 < 8) { const int ai2 = (gi + 1) >> 2, m2 = (gi + 1) & 3; const size_t off2 = (size_t)(row0 + ai2 * HALF + m2 * 16) * DM + col0;
; #pragma unroll
;                 for (int bj = 0; bj < 2; ++bj)
; #pragma unroll
;                     for (int n = 0; n < 2; ++n) xn[bj][n] = *(const f32x4*)(s + off2 + bj * HALF + n * 16); }
; #pragma unroll
;             for (int bj = 0; bj < 2; ++bj)
; #pragma unroll
;                 for (int n = 0; n < 2; ++n) *(f32x4*)(d + off + bj * HALF + n * 16) = xc[bj][n] + gv[bj][n] * acc[ai][bj][m][n];
; #pragma unroll
;             for (int bj = 0; bj < 2; ++bj)
; #pragma unroll
;                 for (int n = 0; n < 2; ++n) xc[bj][n] = xn[bj][n]; }
;     }
	v_pk_fma_f32 v[96:97], v[96:97], v[112:113], v[144:145]
	v_pk_fma_f32 v[94:95], v[94:95], v[110:111], v[142:143]
	v_pk_fma_f32 v[92:93], v[92:93], v[108:109], v[140:141]
	v_pk_fma_f32 v[90:91], v[90:91], v[106:107], v[138:139]
	v_pk_fma_f32 v[80:81], v[80:81], v[104:105], v[136:137]
	v_pk_fma_f32 v[78:79], v[78:79], v[102:103], v[134:135]
	v_pk_fma_f32 v[76:77], v[76:77], v[100:101], v[132:133]
	v_pk_fma_f32 v[74:75], v[74:75], v[98:99], v[130:131]
	global_store_dwordx4 v[114:115], v[94:97], off nt
	global_store_dwordx4 v[114:115], v[90:93], off offset:64 nt
	global_store_dwordx4 v[114:115], v[78:81], off offset:512 nt
	global_store_dwordx4 v[114:115], v[74:77], off offset:576 nt
	v_lshl_add_u64 v[114:115], v[164:165], 0, s[28:29]
	s_mov_b64 s[28:29], s[52:53]
	v_lshl_add_u64 v[74:75], v[160:161], 0, v[114:115]
	global_load_dwordx4 v[94:97], v[74:75], off
	global_load_dwordx4 v[90:93], v[74:75], off offset:64
	global_load_dwordx4 v[78:81], v[74:75], off offset:512
	s_nop 0
	global_load_dwordx4 v[74:77], v[74:75], off offset:576
	v_pk_fma_f32 v[88:89], v[88:89], v[112:113], v[118:119]
	v_pk_fma_f32 v[72:73], v[72:73], v[104:105], v[126:127]
	v_pk_fma_f32 v[68:69], v[68:69], v[100:101], v[156:157]
	v_pk_fma_f32 v[66:67], v[66:67], v[98:99], v[154:155]
	global_store_dwordx4 v[128:129], v[66:69], off offset:576 nt
	v_pk_fma_f32 v[70:71], v[70:71], v[102:103], v[124:125]
	v_pk_fma_f32 v[86:87], v[86:87], v[110:111], v[116:117]
	v_add_u32_e32 v66, 0x90, v162
	v_ashrrev_i32_e32 v67, 31, v66
	v_pk_fma_f32 v[84:85], v[84:85], v[108:109], v[122:123]
	v_pk_fma_f32 v[82:83], v[82:83], v[106:107], v[120:121]
	global_store_dwordx4 v[128:129], v[70:73], off offset:512 nt
	global_store_dwordx4 v[128:129], v[86:89], off nt
	global_store_dwordx4 v[128:129], v[82:85], off offset:64 nt
	v_lshlrev_b64 v[72:73], 13, v[66:67]
	v_lshl_add_u64 v[66:67], v[160:161], 0, v[72:73]
	global_load_dwordx4 v[68:71], v[66:67], off
	global_load_dwordx4 v[82:85], v[66:67], off offset:64
	global_load_dwordx4 v[86:89], v[66:67], off offset:512
	global_load_dwordx4 v[116:119], v[66:67], off offset:576
	v_lshl_add_u64 v[66:67], v[152:153], 0, v[114:115]
	v_lshl_add_u64 v[72:73], v[152:153], 0, v[72:73]
	s_waitcnt vmcnt(0)
	v_pk_fma_f32 v[64:65], v[64:65], v[112:113], v[96:97]
	v_pk_fma_f32 v[62:63], v[62:63], v[110:111], v[94:95]
	v_pk_fma_f32 v[60:61], v[60:61], v[108:109], v[92:93]
	v_pk_fma_f32 v[52:53], v[52:53], v[100:101], v[76:77]
	v_pk_fma_f32 v[50:51], v[50:51], v[98:99], v[74:75]
	global_store_dwordx4 v[66:67], v[50:53], off offset:576 nt
	v_pk_fma_f32 v[58:59], v[58:59], v[106:107], v[90:91]
	v_pk_fma_f32 v[56:57], v[56:57], v[104:105], v[80:81]
	v_add_u32_e32 v50, 0xa0, v162
	v_pk_fma_f32 v[54:55], v[54:55], v[102:103], v[78:79]
	v_ashrrev_i32_e32 v51, 31, v50
	global_store_dwordx4 v[66:67], v[62:65], off nt
	global_store_dwordx4 v[66:67], v[58:61], off offset:64 nt
	global_store_dwordx4 v[66:67], v[54:57], off offset:512 nt
	v_lshlrev_b64 v[66:67], 13, v[50:51]
	v_lshl_add_u64 v[50:51], v[160:161], 0, v[66:67]
	global_load_dwordx4 v[62:65], v[50:51], off
	global_load_dwordx4 v[58:61], v[50:51], off offset:64
	global_load_dwordx4 v[54:57], v[50:51], off offset:512
	s_nop 0
	global_load_dwordx4 v[50:53], v[50:51], off offset:576
	v_pk_fma_f32 v[48:49], v[48:49], v[112:113], v[70:71]
	v_pk_fma_f32 v[46:47], v[46:47], v[110:111], v[68:69]
	v_pk_fma_f32 v[44:45], v[44:45], v[108:109], v[84:85]
	v_pk_fma_f32 v[36:37], v[36:37], v[100:101], v[118:119]
	v_pk_fma_f32 v[34:35], v[34:35], v[98:99], v[116:117]
	global_store_dwordx4 v[72:73], v[34:37], off offset:576 nt
	v_pk_fma_f32 v[42:43], v[42:43], v[106:107], v[82:83]
	v_pk_fma_f32 v[40:41], v[40:41], v[104:105], v[88:89]
	v_add_u32_e32 v34, 0xb0, v162
	v_ashrrev_i32_e32 v35, 31, v34
	v_pk_fma_f32 v[38:39], v[38:39], v[102:103], v[86:87]
	v_lshlrev_b64 v[68:69], 13, v[34:35]
	global_store_dwordx4 v[72:73], v[46:49], off nt
	global_store_dwordx4 v[72:73], v[42:45], off offset:64 nt
	global_store_dwordx4 v[72:73], v[38:41], off offset:512 nt
	v_lshl_add_u64 v[46:47], v[160:161], 0, v[68:69]
	global_load_dwordx4 v[34:37], v[46:47], off
	global_load_dwordx4 v[38:41], v[46:47], off offset:64
	global_load_dwordx4 v[42:45], v[46:47], off offset:512
	s_nop 0
	global_load_dwordx4 v[46:49], v[46:47], off offset:576
	v_lshl_add_u64 v[66:67], v[152:153], 0, v[66:67]
	s_waitcnt vmcnt(0)
	v_pk_fma_f32 v[32:33], v[32:33], v[112:113], v[64:65]
	v_pk_fma_f32 v[30:31], v[30:31], v[110:111], v[62:63]
	v_pk_fma_f32 v[16:17], v[16:17], v[104:105], v[56:57]
	v_pk_fma_f32 v[14:15], v[14:15], v[102:103], v[54:55]
	v_pk_fma_f32 v[12:13], v[12:13], v[100:101], v[52:53]
	v_pk_fma_f32 v[10:11], v[10:11], v[98:99], v[50:51]
	global_store_dwordx4 v[66:67], v[14:17], off offset:512 nt
	global_store_dwordx4 v[66:67], v[10:13], off offset:576 nt
	v_pk_fma_f32 v[28:29], v[28:29], v[108:109], v[60:61]
	v_lshl_add_u64 v[14:15], v[152:153], 0, v[68:69]
	v_pk_fma_f32 v[26:27], v[26:27], v[106:107], v[58:59]
	global_store_dwordx4 v[66:67], v[30:33], off nt
	global_store_dwordx4 v[66:67], v[26:29], off offset:64 nt
	v_pk_fma_f32 v[12:13], v[24:25], v[112:113], v[36:37]
	v_pk_fma_f32 v[10:11], v[22:23], v[110:111], v[34:35]
	global_store_dwordx4 v[14:15], v[10:13], off nt
	v_pk_fma_f32 v[8:9], v[8:9], v[104:105], v[44:45]
	v_pk_fma_f32 v[6:7], v[6:7], v[102:103], v[42:43]
	v_pk_fma_f32 v[12:13], v[20:21], v[108:109], v[40:41]
	v_pk_fma_f32 v[10:11], v[18:19], v[106:107], v[38:39]
	v_pk_fma_f32 v[4:5], v[4:5], v[100:101], v[48:49]
	v_pk_fma_f32 v[2:3], v[2:3], v[98:99], v[46:47]
	global_store_dwordx4 v[14:15], v[10:13], off offset:64 nt
	global_store_dwordx4 v[14:15], v[6:9], off offset:512 nt
	global_store_dwordx4 v[14:15], v[2:5], off offset:576 nt
	s_cbranch_vccnz .LBB0_102
